# PEER apply LN2: gamma fetched with the gate row, beta requested before the reductions (one exposed memory round trip per token instead of three)
# baseline (speedup 1.0000x reference)
; __device__ __forceinline__ void ph_peer_apply(const Params& P, int layer, float* xlat, float* xctx_in, float* xctx_out, int nrows, bool write_next, char* smem, float* xlat_out = nullptr) {
;     ...
;     const float* xs1 = (row < NL ? xlat + (size_t)row * D : xctx_in + (size_t)(row - NL) * D) + lb * 32;
;     float* xo = (row < NL ? (xlat_out ? xlat_out : xlat) + (size_t)row * D : xctx_out + (size_t)(row - NL) * D) + lb * 32;
;     const float* gt = mod_ptr(P, layer, row, 5) + lb * 32;
;     float s = 0.f;
; #pragma unroll
;     for (int j4 = 0; j4 < 8; ++j4) {
;       float4 xa; const float4 ga = *(const float4*)(gt + j4 * 4);
;       if (row < NL) { const h16x4 xh_ = *(const h16x4*)((const h16*)(xlat + (size_t)row * D) + lb * 32 + j4 * 4); xa = make_float4((float)xh_[0], (float)xh_[1], (float)xh_[2], (float)xh_[3]); }
;       else xa = *(const float4*)(xs1 + j4 * 4);
;       o[j4 * 4 + 0] = ALPHA * xa.x + ga.x * o[j4 * 4 + 0]; o[j4 * 4 + 1] = ALPHA * xa.y + ga.y * o[j4 * 4 + 1];
;       o[j4 * 4 + 2] = ALPHA * xa.z + ga.z * o[j4 * 4 + 2]; o[j4 * 4 + 3] = ALPHA * xa.w + ga.w * o[j4 * 4 + 3];
;       s += (o[j4 * 4 + 0] + o[j4 * 4 + 1]) + (o[j4 * 4 + 2] + o[j4 * 4 + 3]);
;     }
.Lav0_cpd:
	s_cmp_ge_u32 s45, 0x8000
	s_cselect_b32 s48, 1, 0
	s_lshr_b32 s49, s45, 14
	s_cmp_lg_u32 s48, 0
	s_cselect_b32 s49, 2, s49
	s_sub_u32 s50, s45, 0x8000
	s_lshl_b32 s15, s45, 13
	s_lshr_b32 s31, s45, 19
	s_add_u32 s40, s6, s15
	s_addc_u32 s41, s7, s31
	s_add_u32 s15, s49, 0
	s_mul_i32 s15, s15, 6
	s_add_u32 s15, s15, 5
	s_lshl_b32 s15, s15, 13
	s_add_u32 s42, s4, 0x4000
	s_addc_u32 s43, s5, 0
	s_add_u32 s42, s42, s15
	s_addc_u32 s43, s43, 0
	global_load_dwordx4 v[112:115], v225, s[42:43]
	global_load_dwordx4 v[116:119], v225, s[42:43] offset:16
	global_load_dwordx4 v[120:123], v225, s[42:43] offset:32
	global_load_dwordx4 v[124:127], v225, s[42:43] offset:48
	global_load_dwordx4 v[128:131], v225, s[42:43] offset:64
	global_load_dwordx4 v[132:135], v225, s[42:43] offset:80
	global_load_dwordx4 v[136:139], v225, s[42:43] offset:96
	global_load_dwordx4 v[140:143], v225, s[42:43] offset:112
	s_add_u32 s26, s8, 0x2000
	s_addc_u32 s27, s9, 0
	global_load_dwordx4 v[80:83], v225, s[26:27]
	global_load_dwordx4 v[84:87], v225, s[26:27] offset:16
	global_load_dwordx4 v[88:91], v225, s[26:27] offset:32
	global_load_dwordx4 v[92:95], v225, s[26:27] offset:48
	global_load_dwordx4 v[96:99], v225, s[26:27] offset:64
	global_load_dwordx4 v[100:103], v225, s[26:27] offset:80
	global_load_dwordx4 v[104:107], v225, s[26:27] offset:96
	global_load_dwordx4 v[108:111], v225, s[26:27] offset:112
	s_mov_b32 s15, 0x3fb504f3
	s_cmp_lg_u32 s48, 0
	s_cbranch_scc1 .Lap0_res_ctx
	global_load_dwordx4 v[192:195], v224, s[40:41]
	global_load_dwordx4 v[196:199], v224, s[40:41] offset:16
	global_load_dwordx4 v[200:203], v224, s[40:41] offset:32
	global_load_dwordx4 v[204:207], v224, s[40:41] offset:48
	s_waitcnt vmcnt(0)
	v_mul_f32_e32 v160, v112, v160
	v_mul_f32_e32 v161, v113, v161
	v_mul_f32_e32 v162, v114, v162
	v_mul_f32_e32 v163, v115, v163
	v_mul_f32_e32 v164, v116, v164
	v_mul_f32_e32 v165, v117, v165
	v_mul_f32_e32 v166, v118, v166
	v_mul_f32_e32 v167, v119, v167
	v_mul_f32_e32 v168, v120, v168
	v_mul_f32_e32 v169, v121, v169
	v_mul_f32_e32 v170, v122, v170
	v_mul_f32_e32 v171, v123, v171
	v_mul_f32_e32 v172, v124, v172
	v_mul_f32_e32 v173, v125, v173
	v_mul_f32_e32 v174, v126, v174
	v_mul_f32_e32 v175, v127, v175
	v_mul_f32_e32 v176, v128, v176
	v_mul_f32_e32 v177, v129, v177
	v_mul_f32_e32 v178, v130, v178
	v_mul_f32_e32 v179, v131, v179
	v_mul_f32_e32 v180, v132, v180
	v_mul_f32_e32 v181, v133, v181
	v_mul_f32_e32 v182, v134, v182
	v_mul_f32_e32 v183, v135, v183
	v_mul_f32_e32 v184, v136, v184
	v_mul_f32_e32 v185, v137, v185
	v_mul_f32_e32 v186, v138, v186
	v_mul_f32_e32 v187, v139, v187
	v_mul_f32_e32 v188, v140, v188
	v_mul_f32_e32 v189, v141, v189
	v_mul_f32_e32 v190, v142, v190
	v_mul_f32_e32 v191, v143, v191
	v_fma_mix_f32 v160, s15, v192, v160 op_sel_hi:[0,1,0]
	v_fma_mix_f32 v161, s15, v192, v161 op_sel:[0,1,0] op_sel_hi:[0,1,0]
	v_fma_mix_f32 v162, s15, v193, v162 op_sel_hi:[0,1,0]
	v_fma_mix_f32 v163, s15, v193, v163 op_sel:[0,1,0] op_sel_hi:[0,1,0]
	v_fma_mix_f32 v164, s15, v194, v164 op_sel_hi:[0,1,0]
	v_fma_mix_f32 v165, s15, v194, v165 op_sel:[0,1,0] op_sel_hi:[0,1,0]
	v_fma_mix_f32 v166, s15, v195, v166 op_sel_hi:[0,1,0]
	v_fma_mix_f32 v167, s15, v195, v167 op_sel:[0,1,0] op_sel_hi:[0,1,0]
	v_fma_mix_f32 v168, s15, v196, v168 op_sel_hi:[0,1,0]
	v_fma_mix_f32 v169, s15, v196, v169 op_sel:[0,1,0] op_sel_hi:[0,1,0]
	v_fma_mix_f32 v170, s15, v197, v170 op_sel_hi:[0,1,0]
	v_fma_mix_f32 v171, s15, v197, v171 op_sel:[0,1,0] op_sel_hi:[0,1,0]
	v_fma_mix_f32 v172, s15, v198, v172 op_sel_hi:[0,1,0]
	v_fma_mix_f32 v173, s15, v198, v173 op_sel:[0,1,0] op_sel_hi:[0,1,0]
	v_fma_mix_f32 v174, s15, v199, v174 op_sel_hi:[0,1,0]
	v_fma_mix_f32 v175, s15, v199, v175 op_sel:[0,1,0] op_sel_hi:[0,1,0]
	v_fma_mix_f32 v176, s15, v200, v176 op_sel_hi:[0,1,0]
	v_fma_mix_f32 v177, s15, v200, v177 op_sel:[0,1,0] op_sel_hi:[0,1,0]
	v_fma_mix_f32 v178, s15, v201, v178 op_sel_hi:[0,1,0]
	v_fma_mix_f32 v179, s15, v201, v179 op_sel:[0,1,0] op_sel_hi:[0,1,0]
	v_fma_mix_f32 v180, s15, v202, v180 op_sel_hi:[0,1,0]
	v_fma_mix_f32 v181, s15, v202, v181 op_sel:[0,1,0] op_sel_hi:[0,1,0]
	v_fma_mix_f32 v182, s15, v203, v182 op_sel_hi:[0,1,0]
	v_fma_mix_f32 v183, s15, v203, v183 op_sel:[0,1,0] op_sel_hi:[0,1,0]
	v_fma_mix_f32 v184, s15, v204, v184 op_sel_hi:[0,1,0]
	v_fma_mix_f32 v185, s15, v204, v185 op_sel:[0,1,0] op_sel_hi:[0,1,0]
	v_fma_mix_f32 v186, s15, v205, v186 op_sel_hi:[0,1,0]
	v_fma_mix_f32 v187, s15, v205, v187 op_sel:[0,1,0] op_sel_hi:[0,1,0]
	v_fma_mix_f32 v188, s15, v206, v188 op_sel_hi:[0,1,0]
	v_fma_mix_f32 v189, s15, v206, v189 op_sel:[0,1,0] op_sel_hi:[0,1,0]
	v_fma_mix_f32 v190, s15, v207, v190 op_sel_hi:[0,1,0]
	v_fma_mix_f32 v191, s15, v207, v191 op_sel:[0,1,0] op_sel_hi:[0,1,0]
	s_branch .Lap0_res_done

; __device__ __forceinline__ float wave_sum(float v) { v = row_sum16(v); v += __shfl_xor(v, 16); v += __shfl_xor(v, 32); return v; }
; __device__ __forceinline__ void ph_peer_apply(const Params& P, int layer, float* xlat, float* xctx_in, float* xctx_out, int nrows, bool write_next, char* smem, float* xlat_out = nullptr) {
;     ...
;     s = wave_sum(lact ? s : 0.f);
;     const float mu = s / (float)D;
;     float s2 = 0.f;
; #pragma unroll
;     for (int j = 0; j < 32; ++j) { const float dd = o[j] - mu; s2 += dd * dd; }
;     s2 = wave_sum(lact ? s2 : 0.f);
;     const float rstd = rsqrtf(s2 / (float)D + LN_EPS);
.Lap0_res_done:
	s_add_u32 s26, s10, 0x2000
	s_addc_u32 s27, s11, 0
	global_load_dwordx4 v[112:115], v225, s[26:27]
	global_load_dwordx4 v[116:119], v225, s[26:27] offset:16
	global_load_dwordx4 v[120:123], v225, s[26:27] offset:32
	global_load_dwordx4 v[124:127], v225, s[26:27] offset:48
	global_load_dwordx4 v[128:131], v225, s[26:27] offset:64
	global_load_dwordx4 v[132:135], v225, s[26:27] offset:80
	global_load_dwordx4 v[136:139], v225, s[26:27] offset:96
	global_load_dwordx4 v[140:143], v225, s[26:27] offset:112
	v_add_f32_e32 v208, v160, v161
	v_add_f32_e32 v208, v208, v162
	v_add_f32_e32 v208, v208, v163
	v_add_f32_e32 v208, v208, v164
	v_add_f32_e32 v208, v208, v165
	v_add_f32_e32 v208, v208, v166
	v_add_f32_e32 v208, v208, v167
	v_add_f32_e32 v208, v208, v168
	v_add_f32_e32 v208, v208, v169
	v_add_f32_e32 v208, v208, v170
	v_add_f32_e32 v208, v208, v171
	v_add_f32_e32 v208, v208, v172
	v_add_f32_e32 v208, v208, v173
	v_add_f32_e32 v208, v208, v174
	v_add_f32_e32 v208, v208, v175
	v_add_f32_e32 v208, v208, v176
	v_add_f32_e32 v208, v208, v177
	v_add_f32_e32 v208, v208, v178
	v_add_f32_e32 v208, v208, v179
	v_add_f32_e32 v208, v208, v180
	v_add_f32_e32 v208, v208, v181
	v_add_f32_e32 v208, v208, v182
	v_add_f32_e32 v208, v208, v183
	v_add_f32_e32 v208, v208, v184
	v_add_f32_e32 v208, v208, v185
	v_add_f32_e32 v208, v208, v186
	v_add_f32_e32 v208, v208, v187
	v_add_f32_e32 v208, v208, v188
	v_add_f32_e32 v208, v208, v189
	v_add_f32_e32 v208, v208, v190
	v_add_f32_e32 v208, v208, v191
	s_nop 1
	v_add_f32_dpp v208, v208, v208 quad_perm:[1,0,3,2] row_mask:0xf bank_mask:0xf bound_ctrl:1
	s_nop 1
	v_add_f32_dpp v208, v208, v208 quad_perm:[2,3,0,1] row_mask:0xf bank_mask:0xf bound_ctrl:1
	s_nop 1
	v_add_f32_dpp v208, v208, v208 row_ror:4 row_mask:0xf bank_mask:0xf bound_ctrl:1
	s_nop 1
	v_add_f32_dpp v208, v208, v208 row_ror:8 row_mask:0xf bank_mask:0xf bound_ctrl:1
	v_mov_b32_e32 v193, v208
	s_nop 1
	v_permlane32_swap_b32_e32 v193, v208
	v_add_f32_e32 v208, v208, v193
	v_mov_b32_e32 v193, v208
	s_nop 1
	v_permlane16_swap_b32_e32 v193, v208
	v_add_f32_e32 v208, v208, v193
	v_mul_f32_e32 v210, 0x3a000000, v208
	v_sub_f32_e32 v160, v160, v210
	v_sub_f32_e32 v161, v161, v210
	v_sub_f32_e32 v162, v162, v210
	v_sub_f32_e32 v163, v163, v210
	v_sub_f32_e32 v164, v164, v210
	v_sub_f32_e32 v165, v165, v210
	v_sub_f32_e32 v166, v166, v210
	v_sub_f32_e32 v167, v167, v210
	v_sub_f32_e32 v168, v168, v210
	v_sub_f32_e32 v169, v169, v210
	v_sub_f32_e32 v170, v170, v210
	v_sub_f32_e32 v171, v171, v210
	v_sub_f32_e32 v172, v172, v210
	v_sub_f32_e32 v173, v173, v210
	v_sub_f32_e32 v174, v174, v210
	v_sub_f32_e32 v175, v175, v210
	v_sub_f32_e32 v176, v176, v210
	v_sub_f32_e32 v177, v177, v210
	v_sub_f32_e32 v178, v178, v210
	v_sub_f32_e32 v179, v179, v210
	v_sub_f32_e32 v180, v180, v210
	v_sub_f32_e32 v181, v181, v210
	v_sub_f32_e32 v182, v182, v210
	v_sub_f32_e32 v183, v183, v210
	v_sub_f32_e32 v184, v184, v210
	v_sub_f32_e32 v185, v185, v210
	v_sub_f32_e32 v186, v186, v210
	v_sub_f32_e32 v187, v187, v210
	v_sub_f32_e32 v188, v188, v210
	v_sub_f32_e32 v189, v189, v210
	v_sub_f32_e32 v190, v190, v210
	v_sub_f32_e32 v191, v191, v210
	v_mul_f32_e32 v209, v160, v160
	v_fmac_f32_e32 v209, v161, v161
	v_fmac_f32_e32 v209, v162, v162
	v_fmac_f32_e32 v209, v163, v163
	v_fmac_f32_e32 v209, v164, v164
	v_fmac_f32_e32 v209, v165, v165
	v_fmac_f32_e32 v209, v166, v166
	v_fmac_f32_e32 v209, v167, v167
	v_fmac_f32_e32 v209, v168, v168
	v_fmac_f32_e32 v209, v169, v169
	v_fmac_f32_e32 v209, v170, v170
	v_fmac_f32_e32 v209, v171, v171
	v_fmac_f32_e32 v209, v172, v172
	v_fmac_f32_e32 v209, v173, v173
	v_fmac_f32_e32 v209, v174, v174
	v_fmac_f32_e32 v209, v175, v175
	v_fmac_f32_e32 v209, v176, v176
	v_fmac_f32_e32 v209, v177, v177
	v_fmac_f32_e32 v209, v178, v178
	v_fmac_f32_e32 v209, v179, v179
	v_fmac_f32_e32 v209, v180, v180
	v_fmac_f32_e32 v209, v181, v181
	v_fmac_f32_e32 v209, v182, v182
	v_fmac_f32_e32 v209, v183, v183
	v_fmac_f32_e32 v209, v184, v184
	v_fmac_f32_e32 v209, v185, v185
	v_fmac_f32_e32 v209, v186, v186
	v_fmac_f32_e32 v209, v187, v187
	v_fmac_f32_e32 v209, v188, v188
	v_fmac_f32_e32 v209, v189, v189
	v_fmac_f32_e32 v209, v190, v190
	v_fmac_f32_e32 v209, v191, v191
	s_nop 1
	v_add_f32_dpp v209, v209, v209 quad_perm:[1,0,3,2] row_mask:0xf bank_mask:0xf bound_ctrl:1
	s_nop 1
	v_add_f32_dpp v209, v209, v209 quad_perm:[2,3,0,1] row_mask:0xf bank_mask:0xf bound_ctrl:1
	s_nop 1
	v_add_f32_dpp v209, v209, v209 row_ror:4 row_mask:0xf bank_mask:0xf bound_ctrl:1
	s_nop 1
	v_add_f32_dpp v209, v209, v209 row_ror:8 row_mask:0xf bank_mask:0xf bound_ctrl:1
	v_mov_b32_e32 v193, v209
	s_nop 1
	v_permlane32_swap_b32_e32 v193, v209
	v_add_f32_e32 v209, v209, v193
	v_mov_b32_e32 v193, v209
	s_nop 1
	v_permlane16_swap_b32_e32 v193, v209
	v_add_f32_e32 v209, v209, v193
	v_mov_b32_e32 v211, 0x3727c5ac
	v_fmac_f32_e32 v211, 0x3a000000, v209
	v_rsq_f32_e32 v211, v211
	s_waitcnt vmcnt(0)
; __device__ __forceinline__ void ph_peer_apply(const Params& P, int layer, float* xlat, float* xctx_in, float* xctx_out, int nrows, bool write_next, char* smem, float* xlat_out = nullptr) {
;     ...
;     if (lact) {
; #pragma unroll
;       for (int j4 = 0; j4 < 8; ++j4) {
;         const float4 gv = *(const float4*)(gp + j4 * 4), bv = *(const float4*)(bp + j4 * 4);
;         float4 ov;
;         ov.x = (o[j4 * 4 + 0] - mu) * rstd * gv.x + bv.x; ov.y = (o[j4 * 4 + 1] - mu) * rstd * gv.y + bv.y;
;         ov.z = (o[j4 * 4 + 2] - mu) * rstd * gv.z + bv.z; ov.w = (o[j4 * 4 + 3] - mu) * rstd * gv.w + bv.w;
;         if (row < NL && write_next) { h16x4 oh_; oh_[0] = (h16)ov.x; oh_[1] = (h16)ov.y; oh_[2] = (h16)ov.z; oh_[3] = (h16)ov.w; *(h16x4*)((h16*)((xlat_out ? xlat_out : xlat) + (size_t)row * D) + lb * 32 + j4 * 4) = oh_; }
	v_mul_f32_e32 v160, v160, v211
	v_mul_f32_e32 v161, v161, v211
	v_mul_f32_e32 v162, v162, v211
	v_mul_f32_e32 v163, v163, v211
	v_mul_f32_e32 v164, v164, v211
	v_mul_f32_e32 v165, v165, v211
	v_mul_f32_e32 v166, v166, v211
	v_mul_f32_e32 v167, v167, v211
	v_mul_f32_e32 v168, v168, v211
	v_mul_f32_e32 v169, v169, v211
	v_mul_f32_e32 v170, v170, v211
	v_mul_f32_e32 v171, v171, v211
	v_mul_f32_e32 v172, v172, v211
	v_mul_f32_e32 v173, v173, v211
	v_mul_f32_e32 v174, v174, v211
	v_mul_f32_e32 v175, v175, v211
	v_mul_f32_e32 v176, v176, v211
	v_mul_f32_e32 v177, v177, v211
	v_mul_f32_e32 v178, v178, v211
	v_mul_f32_e32 v179, v179, v211
	v_mul_f32_e32 v180, v180, v211
	v_mul_f32_e32 v181, v181, v211
	v_mul_f32_e32 v182, v182, v211
	v_mul_f32_e32 v183, v183, v211
	v_mul_f32_e32 v184, v184, v211
	v_mul_f32_e32 v185, v185, v211
	v_mul_f32_e32 v186, v186, v211
	v_mul_f32_e32 v187, v187, v211
	v_mul_f32_e32 v188, v188, v211
	v_mul_f32_e32 v189, v189, v211
	v_mul_f32_e32 v190, v190, v211
	v_mul_f32_e32 v191, v191, v211
	v_mul_f32_e32 v160, v160, v80
	v_mul_f32_e32 v161, v161, v81
	v_mul_f32_e32 v162, v162, v82
	v_mul_f32_e32 v163, v163, v83
	v_mul_f32_e32 v164, v164, v84
	v_mul_f32_e32 v165, v165, v85
	v_mul_f32_e32 v166, v166, v86
	v_mul_f32_e32 v167, v167, v87
	v_mul_f32_e32 v168, v168, v88
	v_mul_f32_e32 v169, v169, v89
	v_mul_f32_e32 v170, v170, v90
	v_mul_f32_e32 v171, v171, v91
	v_mul_f32_e32 v172, v172, v92
	v_mul_f32_e32 v173, v173, v93
	v_mul_f32_e32 v174, v174, v94
	v_mul_f32_e32 v175, v175, v95
	v_mul_f32_e32 v176, v176, v96
	v_mul_f32_e32 v177, v177, v97
	v_mul_f32_e32 v178, v178, v98
	v_mul_f32_e32 v179, v179, v99
	v_mul_f32_e32 v180, v180, v100
	v_mul_f32_e32 v181, v181, v101
	v_mul_f32_e32 v182, v182, v102
	v_mul_f32_e32 v183, v183, v103
	v_mul_f32_e32 v184, v184, v104
	v_mul_f32_e32 v185, v185, v105
	v_mul_f32_e32 v186, v186, v106
	v_mul_f32_e32 v187, v187, v107
	v_mul_f32_e32 v188, v188, v108
	v_mul_f32_e32 v189, v189, v109
	v_mul_f32_e32 v190, v190, v110
	v_mul_f32_e32 v191, v191, v111
	v_add_f32_e32 v160, v160, v112
	v_add_f32_e32 v161, v161, v113
	v_add_f32_e32 v162, v162, v114
	v_add_f32_e32 v163, v163, v115
	v_add_f32_e32 v164, v164, v116
	v_add_f32_e32 v165, v165, v117
	v_add_f32_e32 v166, v166, v118
	v_add_f32_e32 v167, v167, v119
	v_add_f32_e32 v168, v168, v120
	v_add_f32_e32 v169, v169, v121
	v_add_f32_e32 v170, v170, v122
	v_add_f32_e32 v171, v171, v123
	v_add_f32_e32 v172, v172, v124
	v_add_f32_e32 v173, v173, v125
	v_add_f32_e32 v174, v174, v126
	v_add_f32_e32 v175, v175, v127
	v_add_f32_e32 v176, v176, v128
	v_add_f32_e32 v177, v177, v129
	v_add_f32_e32 v178, v178, v130
	v_add_f32_e32 v179, v179, v131
	v_add_f32_e32 v180, v180, v132
	v_add_f32_e32 v181, v181, v133
	v_add_f32_e32 v182, v182, v134
	v_add_f32_e32 v183, v183, v135
	v_add_f32_e32 v184, v184, v136
	v_add_f32_e32 v185, v185, v137
	v_add_f32_e32 v186, v186, v138
	v_add_f32_e32 v187, v187, v139
	v_add_f32_e32 v188, v188, v140
	v_add_f32_e32 v189, v189, v141
	v_add_f32_e32 v190, v190, v142
	v_add_f32_e32 v191, v191, v143
	s_cmp_lg_u32 s48, 0
	s_cbranch_scc1 .Lap0_out_ctx
	v_cvt_pk_f16_f32 v192, v160, v161
	v_cvt_pk_f16_f32 v193, v162, v163
	v_cvt_pk_f16_f32 v194, v164, v165
	v_cvt_pk_f16_f32 v195, v166, v167
	v_cvt_pk_f16_f32 v196, v168, v169
	v_cvt_pk_f16_f32 v197, v170, v171
	v_cvt_pk_f16_f32 v198, v172, v173
	v_cvt_pk_f16_f32 v199, v174, v175
	v_cvt_pk_f16_f32 v200, v176, v177
	v_cvt_pk_f16_f32 v201, v178, v179
	v_cvt_pk_f16_f32 v202, v180, v181
	v_cvt_pk_f16_f32 v203, v182, v183
	v_cvt_pk_f16_f32 v204, v184, v185
	v_cvt_pk_f16_f32 v205, v186, v187
	v_cvt_pk_f16_f32 v206, v188, v189
	v_cvt_pk_f16_f32 v207, v190, v191
	global_store_dwordx4 v224, v[192:195], s[40:41]
	global_store_dwordx4 v224, v[196:199], s[40:41] offset:16
	global_store_dwordx4 v224, v[200:203], s[40:41] offset:32
	global_store_dwordx4 v224, v[204:207], s[40:41] offset:48
	s_branch .Lap0_out_done

; __device__ __forceinline__ float wave_sum(float v) { v = row_sum16(v); v += __shfl_xor(v, 16); v += __shfl_xor(v, 32); return v; }
; __device__ __forceinline__ void ph_peer_apply(const Params& P, int layer, float* xlat, float* xctx_in, float* xctx_out, int nrows, bool write_next, char* smem, float* xlat_out = nullptr) {
;     ...
;     const float* xs1 = (row < NL ? xlat + (size_t)row * D : xctx_in + (size_t)(row - NL) * D) + lb * 32;
;     float* xo = (row < NL ? (xlat_out ? xlat_out : xlat) + (size_t)row * D : xctx_out + (size_t)(row - NL) * D) + lb * 32;
;     const float* gt = mod_ptr(P, layer, row, 5) + lb * 32;
;     float s = 0.f;
; #pragma unroll
;     for (int j4 = 0; j4 < 8; ++j4) {
;       float4 xa; const float4 ga = *(const float4*)(gt + j4 * 4);
;       if (row < NL) { const h16x4 xh_ = *(const h16x4*)((const h16*)(xlat + (size_t)row * D) + lb * 32 + j4 * 4); xa = make_float4((float)xh_[0], (float)xh_[1], (float)xh_[2], (float)xh_[3]); }
;       else xa = *(const float4*)(xs1 + j4 * 4);
;       o[j4 * 4 + 0] = ALPHA * xa.x + ga.x * o[j4 * 4 + 0]; o[j4 * 4 + 1] = ALPHA * xa.y + ga.y * o[j4 * 4 + 1];
;       o[j4 * 4 + 2] = ALPHA * xa.z + ga.z * o[j4 * 4 + 2]; o[j4 * 4 + 3] = ALPHA * xa.w + ga.w * o[j4 * 4 + 3];
;       s += (o[j4 * 4 + 0] + o[j4 * 4 + 1]) + (o[j4 * 4 + 2] + o[j4 * 4 + 3]);
;     }
;     s = wave_sum(lact ? s : 0.f);
.Lav1_cpd:
	s_cmp_ge_u32 s45, 0x8000
	s_cselect_b32 s48, 1, 0
	s_lshr_b32 s49, s45, 14
	s_cmp_lg_u32 s48, 0
	s_cselect_b32 s49, 2, s49
	s_sub_u32 s50, s45, 0x8000
	s_lshl_b32 s15, s45, 13
	s_lshr_b32 s31, s45, 19
	s_add_u32 s40, s6, s15
	s_addc_u32 s41, s7, s31
	s_add_u32 s15, s49, 3
	s_mul_i32 s15, s15, 6
	s_add_u32 s15, s15, 5
	s_lshl_b32 s15, s15, 13
	s_add_u32 s42, s4, 0x4000
	s_addc_u32 s43, s5, 0
	s_add_u32 s42, s42, s15
	s_addc_u32 s43, s43, 0
	global_load_dwordx4 v[112:115], v225, s[42:43]
	global_load_dwordx4 v[116:119], v225, s[42:43] offset:16
	global_load_dwordx4 v[120:123], v225, s[42:43] offset:32
	global_load_dwordx4 v[124:127], v225, s[42:43] offset:48
	global_load_dwordx4 v[128:131], v225, s[42:43] offset:64
	global_load_dwordx4 v[132:135], v225, s[42:43] offset:80
	global_load_dwordx4 v[136:139], v225, s[42:43] offset:96
	global_load_dwordx4 v[140:143], v225, s[42:43] offset:112
	s_add_u32 s26, s8, 0x6000
	s_addc_u32 s27, s9, 0
	global_load_dwordx4 v[80:83], v225, s[26:27]
	global_load_dwordx4 v[84:87], v225, s[26:27] offset:16
	global_load_dwordx4 v[88:91], v225, s[26:27] offset:32
	global_load_dwordx4 v[92:95], v225, s[26:27] offset:48
	global_load_dwordx4 v[96:99], v225, s[26:27] offset:64
	global_load_dwordx4 v[100:103], v225, s[26:27] offset:80
	global_load_dwordx4 v[104:107], v225, s[26:27] offset:96
	global_load_dwordx4 v[108:111], v225, s[26:27] offset:112
	s_mov_b32 s15, 0x3fb504f3
	global_load_dwordx4 v[192:195], v224, s[40:41]
	global_load_dwordx4 v[196:199], v224, s[40:41] offset:16
	global_load_dwordx4 v[200:203], v224, s[40:41] offset:32
	global_load_dwordx4 v[204:207], v224, s[40:41] offset:48
	s_waitcnt vmcnt(0)
	v_mul_f32_e32 v160, v112, v160
	v_mul_f32_e32 v161, v113, v161
	v_mul_f32_e32 v162, v114, v162
	v_mul_f32_e32 v163, v115, v163
	v_mul_f32_e32 v164, v116, v164
	v_mul_f32_e32 v165, v117, v165
	v_mul_f32_e32 v166, v118, v166
	v_mul_f32_e32 v167, v119, v167
	v_mul_f32_e32 v168, v120, v168
	v_mul_f32_e32 v169, v121, v169
	v_mul_f32_e32 v170, v122, v170
	v_mul_f32_e32 v171, v123, v171
	v_mul_f32_e32 v172, v124, v172
	v_mul_f32_e32 v173, v125, v173
	v_mul_f32_e32 v174, v126, v174
	v_mul_f32_e32 v175, v127, v175
	v_mul_f32_e32 v176, v128, v176
	v_mul_f32_e32 v177, v129, v177
	v_mul_f32_e32 v178, v130, v178
	v_mul_f32_e32 v179, v131, v179
	v_mul_f32_e32 v180, v132, v180
	v_mul_f32_e32 v181, v133, v181
	v_mul_f32_e32 v182, v134, v182
	v_mul_f32_e32 v183, v135, v183
	v_mul_f32_e32 v184, v136, v184
	v_mul_f32_e32 v185, v137, v185
	v_mul_f32_e32 v186, v138, v186
	v_mul_f32_e32 v187, v139, v187
	v_mul_f32_e32 v188, v140, v188
	v_mul_f32_e32 v189, v141, v189
	v_mul_f32_e32 v190, v142, v190
	v_mul_f32_e32 v191, v143, v191
	v_fma_mix_f32 v160, s15, v192, v160 op_sel_hi:[0,1,0]
	v_fma_mix_f32 v161, s15, v192, v161 op_sel:[0,1,0] op_sel_hi:[0,1,0]
	v_fma_mix_f32 v162, s15, v193, v162 op_sel_hi:[0,1,0]
	v_fma_mix_f32 v163, s15, v193, v163 op_sel:[0,1,0] op_sel_hi:[0,1,0]
	v_fma_mix_f32 v164, s15, v194, v164 op_sel_hi:[0,1,0]
	v_fma_mix_f32 v165, s15, v194, v165 op_sel:[0,1,0] op_sel_hi:[0,1,0]
	v_fma_mix_f32 v166, s15, v195, v166 op_sel_hi:[0,1,0]
	v_fma_mix_f32 v167, s15, v195, v167 op_sel:[0,1,0] op_sel_hi:[0,1,0]
	v_fma_mix_f32 v168, s15, v196, v168 op_sel_hi:[0,1,0]
	v_fma_mix_f32 v169, s15, v196, v169 op_sel:[0,1,0] op_sel_hi:[0,1,0]
	v_fma_mix_f32 v170, s15, v197, v170 op_sel_hi:[0,1,0]
	v_fma_mix_f32 v171, s15, v197, v171 op_sel:[0,1,0] op_sel_hi:[0,1,0]
	v_fma_mix_f32 v172, s15, v198, v172 op_sel_hi:[0,1,0]
	v_fma_mix_f32 v173, s15, v198, v173 op_sel:[0,1,0] op_sel_hi:[0,1,0]
	v_fma_mix_f32 v174, s15, v199, v174 op_sel_hi:[0,1,0]
	v_fma_mix_f32 v175, s15, v199, v175 op_sel:[0,1,0] op_sel_hi:[0,1,0]
	v_fma_mix_f32 v176, s15, v200, v176 op_sel_hi:[0,1,0]
	v_fma_mix_f32 v177, s15, v200, v177 op_sel:[0,1,0] op_sel_hi:[0,1,0]
	v_fma_mix_f32 v178, s15, v201, v178 op_sel_hi:[0,1,0]
	v_fma_mix_f32 v179, s15, v201, v179 op_sel:[0,1,0] op_sel_hi:[0,1,0]
	v_fma_mix_f32 v180, s15, v202, v180 op_sel_hi:[0,1,0]
	v_fma_mix_f32 v181, s15, v202, v181 op_sel:[0,1,0] op_sel_hi:[0,1,0]
	v_fma_mix_f32 v182, s15, v203, v182 op_sel_hi:[0,1,0]
	v_fma_mix_f32 v183, s15, v203, v183 op_sel:[0,1,0] op_sel_hi:[0,1,0]
	v_fma_mix_f32 v184, s15, v204, v184 op_sel_hi:[0,1,0]
	v_fma_mix_f32 v185, s15, v204, v185 op_sel:[0,1,0] op_sel_hi:[0,1,0]
	v_fma_mix_f32 v186, s15, v205, v186 op_sel_hi:[0,1,0]
	v_fma_mix_f32 v187, s15, v205, v187 op_sel:[0,1,0] op_sel_hi:[0,1,0]
	v_fma_mix_f32 v188, s15, v206, v188 op_sel_hi:[0,1,0]
	v_fma_mix_f32 v189, s15, v206, v189 op_sel:[0,1,0] op_sel_hi:[0,1,0]
	v_fma_mix_f32 v190, s15, v207, v190 op_sel_hi:[0,1,0]
	v_fma_mix_f32 v191, s15, v207, v191 op_sel:[0,1,0] op_sel_hi:[0,1,0]
	s_add_u32 s26, s10, 0x6000
	s_addc_u32 s27, s11, 0
	global_load_dwordx4 v[112:115], v225, s[26:27]
	global_load_dwordx4 v[116:119], v225, s[26:27] offset:16
	global_load_dwordx4 v[120:123], v225, s[26:27] offset:32
	global_load_dwordx4 v[124:127], v225, s[26:27] offset:48
	global_load_dwordx4 v[128:131], v225, s[26:27] offset:64
	global_load_dwordx4 v[132:135], v225, s[26:27] offset:80
	global_load_dwordx4 v[136:139], v225, s[26:27] offset:96
	global_load_dwordx4 v[140:143], v225, s[26:27] offset:112
	v_add_f32_e32 v208, v160, v161
	v_add_f32_e32 v208, v208, v162
	v_add_f32_e32 v208, v208, v163
	v_add_f32_e32 v208, v208, v164
	v_add_f32_e32 v208, v208, v165
	v_add_f32_e32 v208, v208, v166
	v_add_f32_e32 v208, v208, v167
	v_add_f32_e32 v208, v208, v168
	v_add_f32_e32 v208, v208, v169
	v_add_f32_e32 v208, v208, v170
	v_add_f32_e32 v208, v208, v171
	v_add_f32_e32 v208, v208, v172
	v_add_f32_e32 v208, v208, v173
	v_add_f32_e32 v208, v208, v174
; __device__ __forceinline__ float wave_sum(float v) { v = row_sum16(v); v += __shfl_xor(v, 16); v += __shfl_xor(v, 32); return v; }
; __device__ __forceinline__ void ph_peer_apply(const Params& P, int layer, float* xlat, float* xctx_in, float* xctx_out, int nrows, bool write_next, char* smem, float* xlat_out = nullptr) {
;     ...
;     s = wave_sum(lact ? s : 0.f);
;     const float mu = s / (float)D;
;     float s2 = 0.f;
; #pragma unroll
;     for (int j = 0; j < 32; ++j) { const float dd = o[j] - mu; s2 += dd * dd; }
;     s2 = wave_sum(lact ? s2 : 0.f);
;     const float rstd = rsqrtf(s2 / (float)D + LN_EPS);
	v_add_f32_e32 v208, v208, v175
	v_add_f32_e32 v208, v208, v176
	v_add_f32_e32 v208, v208, v177
	v_add_f32_e32 v208, v208, v178
	v_add_f32_e32 v208, v208, v179
	v_add_f32_e32 v208, v208, v180
	v_add_f32_e32 v208, v208, v181
	v_add_f32_e32 v208, v208, v182
	v_add_f32_e32 v208, v208, v183
	v_add_f32_e32 v208, v208, v184
	v_add_f32_e32 v208, v208, v185
	v_add_f32_e32 v208, v208, v186
	v_add_f32_e32 v208, v208, v187
	v_add_f32_e32 v208, v208, v188
	v_add_f32_e32 v208, v208, v189
	v_add_f32_e32 v208, v208, v190
	v_add_f32_e32 v208, v208, v191
	s_nop 1
	v_add_f32_dpp v208, v208, v208 quad_perm:[1,0,3,2] row_mask:0xf bank_mask:0xf bound_ctrl:1
	s_nop 1
	v_add_f32_dpp v208, v208, v208 quad_perm:[2,3,0,1] row_mask:0xf bank_mask:0xf bound_ctrl:1
	s_nop 1
	v_add_f32_dpp v208, v208, v208 row_ror:4 row_mask:0xf bank_mask:0xf bound_ctrl:1
	s_nop 1
	v_add_f32_dpp v208, v208, v208 row_ror:8 row_mask:0xf bank_mask:0xf bound_ctrl:1
	v_mov_b32_e32 v193, v208
	s_nop 1
	v_permlane32_swap_b32_e32 v193, v208
	v_add_f32_e32 v208, v208, v193
	v_mov_b32_e32 v193, v208
	s_nop 1
	v_permlane16_swap_b32_e32 v193, v208
	v_add_f32_e32 v208, v208, v193
	v_mul_f32_e32 v210, 0x3a000000, v208
	v_sub_f32_e32 v160, v160, v210
	v_sub_f32_e32 v161, v161, v210
	v_sub_f32_e32 v162, v162, v210
	v_sub_f32_e32 v163, v163, v210
	v_sub_f32_e32 v164, v164, v210
	v_sub_f32_e32 v165, v165, v210
	v_sub_f32_e32 v166, v166, v210
	v_sub_f32_e32 v167, v167, v210
	v_sub_f32_e32 v168, v168, v210
	v_sub_f32_e32 v169, v169, v210
	v_sub_f32_e32 v170, v170, v210
	v_sub_f32_e32 v171, v171, v210
	v_sub_f32_e32 v172, v172, v210
	v_sub_f32_e32 v173, v173, v210
	v_sub_f32_e32 v174, v174, v210
	v_sub_f32_e32 v175, v175, v210
	v_sub_f32_e32 v176, v176, v210
	v_sub_f32_e32 v177, v177, v210
	v_sub_f32_e32 v178, v178, v210
	v_sub_f32_e32 v179, v179, v210
	v_sub_f32_e32 v180, v180, v210
	v_sub_f32_e32 v181, v181, v210
	v_sub_f32_e32 v182, v182, v210
	v_sub_f32_e32 v183, v183, v210
	v_sub_f32_e32 v184, v184, v210
	v_sub_f32_e32 v185, v185, v210
	v_sub_f32_e32 v186, v186, v210
	v_sub_f32_e32 v187, v187, v210
	v_sub_f32_e32 v188, v188, v210
	v_sub_f32_e32 v189, v189, v210
	v_sub_f32_e32 v190, v190, v210
	v_sub_f32_e32 v191, v191, v210
	v_mul_f32_e32 v209, v160, v160
	v_fmac_f32_e32 v209, v161, v161
	v_fmac_f32_e32 v209, v162, v162
	v_fmac_f32_e32 v209, v163, v163
	v_fmac_f32_e32 v209, v164, v164
	v_fmac_f32_e32 v209, v165, v165
	v_fmac_f32_e32 v209, v166, v166
	v_fmac_f32_e32 v209, v167, v167
	v_fmac_f32_e32 v209, v168, v168
	v_fmac_f32_e32 v209, v169, v169
	v_fmac_f32_e32 v209, v170, v170
	v_fmac_f32_e32 v209, v171, v171
	v_fmac_f32_e32 v209, v172, v172
	v_fmac_f32_e32 v209, v173, v173
	v_fmac_f32_e32 v209, v174, v174
	v_fmac_f32_e32 v209, v175, v175
	v_fmac_f32_e32 v209, v176, v176
	v_fmac_f32_e32 v209, v177, v177
	v_fmac_f32_e32 v209, v178, v178
	v_fmac_f32_e32 v209, v179, v179
	v_fmac_f32_e32 v209, v180, v180
	v_fmac_f32_e32 v209, v181, v181
	v_fmac_f32_e32 v209, v182, v182
	v_fmac_f32_e32 v209, v183, v183
	v_fmac_f32_e32 v209, v184, v184
	v_fmac_f32_e32 v209, v185, v185
	v_fmac_f32_e32 v209, v186, v186
	v_fmac_f32_e32 v209, v187, v187
	v_fmac_f32_e32 v209, v188, v188
	v_fmac_f32_e32 v209, v189, v189
	v_fmac_f32_e32 v209, v190, v190
	v_fmac_f32_e32 v209, v191, v191
	s_nop 1
	v_add_f32_dpp v209, v209, v209 quad_perm:[1,0,3,2] row_mask:0xf bank_mask:0xf bound_ctrl:1
	s_nop 1
	v_add_f32_dpp v209, v209, v209 quad_perm:[2,3,0,1] row_mask:0xf bank_mask:0xf bound_ctrl:1
	s_nop 1
	v_add_f32_dpp v209, v209, v209 row_ror:4 row_mask:0xf bank_mask:0xf bound_ctrl:1
	s_nop 1
	v_add_f32_dpp v209, v209, v209 row_ror:8 row_mask:0xf bank_mask:0xf bound_ctrl:1
	v_mov_b32_e32 v193, v209
	s_nop 1
	v_permlane32_swap_b32_e32 v193, v209
	v_add_f32_e32 v209, v209, v193
	v_mov_b32_e32 v193, v209
	s_nop 1
	v_permlane16_swap_b32_e32 v193, v209
	v_add_f32_e32 v209, v209, v193
	v_mov_b32_e32 v211, 0x3727c5ac
	v_fmac_f32_e32 v211, 0x3a000000, v209
	v_rsq_f32_e32 v211, v211
	s_waitcnt vmcnt(0)
; __device__ __forceinline__ void ph_peer_apply(const Params& P, int layer, float* xlat, float* xctx_in, float* xctx_out, int nrows, bool write_next, char* smem, float* xlat_out = nullptr) {
;     ...
;     if (lact) {
; #pragma unroll
;       for (int j4 = 0; j4 < 8; ++j4) {
;         const float4 gv = *(const float4*)(gp + j4 * 4), bv = *(const float4*)(bp + j4 * 4);
;         float4 ov;
;         ov.x = (o[j4 * 4 + 0] - mu) * rstd * gv.x + bv.x; ov.y = (o[j4 * 4 + 1] - mu) * rstd * gv.y + bv.y;
;         ov.z = (o[j4 * 4 + 2] - mu) * rstd * gv.z + bv.z; ov.w = (o[j4 * 4 + 3] - mu) * rstd * gv.w + bv.w;
;         if (row < NL && write_next) { h16x4 oh_; oh_[0] = (h16)ov.x; oh_[1] = (h16)ov.y; oh_[2] = (h16)ov.z; oh_[3] = (h16)ov.w; *(h16x4*)((h16*)((xlat_out ? xlat_out : xlat) + (size_t)row * D) + lb * 32 + j4 * 4) = oh_; }
;         else *(float4*)(xo + j4 * 4) = ov;
	v_mul_f32_e32 v160, v160, v211
	v_mul_f32_e32 v161, v161, v211
	v_mul_f32_e32 v162, v162, v211
	v_mul_f32_e32 v163, v163, v211
	v_mul_f32_e32 v164, v164, v211
	v_mul_f32_e32 v165, v165, v211
	v_mul_f32_e32 v166, v166, v211
	v_mul_f32_e32 v167, v167, v211
	v_mul_f32_e32 v168, v168, v211
	v_mul_f32_e32 v169, v169, v211
	v_mul_f32_e32 v170, v170, v211
	v_mul_f32_e32 v171, v171, v211
	v_mul_f32_e32 v172, v172, v211
	v_mul_f32_e32 v173, v173, v211
	v_mul_f32_e32 v174, v174, v211
	v_mul_f32_e32 v175, v175, v211
	v_mul_f32_e32 v176, v176, v211
	v_mul_f32_e32 v177, v177, v211
	v_mul_f32_e32 v178, v178, v211
	v_mul_f32_e32 v179, v179, v211
	v_mul_f32_e32 v180, v180, v211
	v_mul_f32_e32 v181, v181, v211
	v_mul_f32_e32 v182, v182, v211
	v_mul_f32_e32 v183, v183, v211
	v_mul_f32_e32 v184, v184, v211
	v_mul_f32_e32 v185, v185, v211
	v_mul_f32_e32 v186, v186, v211
	v_mul_f32_e32 v187, v187, v211
	v_mul_f32_e32 v188, v188, v211
	v_mul_f32_e32 v189, v189, v211
	v_mul_f32_e32 v190, v190, v211
	v_mul_f32_e32 v191, v191, v211
	v_mul_f32_e32 v160, v160, v80
	v_mul_f32_e32 v161, v161, v81
	v_mul_f32_e32 v162, v162, v82
	v_mul_f32_e32 v163, v163, v83
	v_mul_f32_e32 v164, v164, v84
	v_mul_f32_e32 v165, v165, v85
	v_mul_f32_e32 v166, v166, v86
	v_mul_f32_e32 v167, v167, v87
	v_mul_f32_e32 v168, v168, v88
	v_mul_f32_e32 v169, v169, v89
	v_mul_f32_e32 v170, v170, v90
	v_mul_f32_e32 v171, v171, v91
	v_mul_f32_e32 v172, v172, v92
	v_mul_f32_e32 v173, v173, v93
	v_mul_f32_e32 v174, v174, v94
	v_mul_f32_e32 v175, v175, v95
	v_mul_f32_e32 v176, v176, v96
	v_mul_f32_e32 v177, v177, v97
	v_mul_f32_e32 v178, v178, v98
	v_mul_f32_e32 v179, v179, v99
	v_mul_f32_e32 v180, v180, v100
	v_mul_f32_e32 v181, v181, v101
	v_mul_f32_e32 v182, v182, v102
	v_mul_f32_e32 v183, v183, v103
	v_mul_f32_e32 v184, v184, v104
	v_mul_f32_e32 v185, v185, v105
	v_mul_f32_e32 v186, v186, v106
	v_mul_f32_e32 v187, v187, v107
	v_mul_f32_e32 v188, v188, v108
	v_mul_f32_e32 v189, v189, v109
	v_mul_f32_e32 v190, v190, v110
	v_mul_f32_e32 v191, v191, v111
	v_add_f32_e32 v160, v160, v112
	v_add_f32_e32 v161, v161, v113
	v_add_f32_e32 v162, v162, v114
	v_add_f32_e32 v163, v163, v115
	v_add_f32_e32 v164, v164, v116
	v_add_f32_e32 v165, v165, v117
	v_add_f32_e32 v166, v166, v118
	v_add_f32_e32 v167, v167, v119
	v_add_f32_e32 v168, v168, v120
	v_add_f32_e32 v169, v169, v121
	v_add_f32_e32 v170, v170, v122
	v_add_f32_e32 v171, v171, v123
	v_add_f32_e32 v172, v172, v124
	v_add_f32_e32 v173, v173, v125
	v_add_f32_e32 v174, v174, v126
	v_add_f32_e32 v175, v175, v127
	v_add_f32_e32 v176, v176, v128
	v_add_f32_e32 v177, v177, v129
	v_add_f32_e32 v178, v178, v130
	v_add_f32_e32 v179, v179, v131
	v_add_f32_e32 v180, v180, v132
	v_add_f32_e32 v181, v181, v133
	v_add_f32_e32 v182, v182, v134
	v_add_f32_e32 v183, v183, v135
	v_add_f32_e32 v184, v184, v136
	v_add_f32_e32 v185, v185, v137
	v_add_f32_e32 v186, v186, v138
	v_add_f32_e32 v187, v187, v139
	v_add_f32_e32 v188, v188, v140
	v_add_f32_e32 v189, v189, v141
	v_add_f32_e32 v190, v190, v142
	v_add_f32_e32 v191, v191, v143
	global_store_dwordx4 v225, v[160:163], s[40:41]
	global_store_dwordx4 v225, v[164:167], s[40:41] offset:16
	global_store_dwordx4 v225, v[168:171], s[40:41] offset:32
	global_store_dwordx4 v225, v[172:175], s[40:41] offset:48
	global_store_dwordx4 v225, v[176:179], s[40:41] offset:64
	global_store_dwordx4 v225, v[180:183], s[40:41] offset:80
	global_store_dwordx4 v225, v[184:187], s[40:41] offset:96
	global_store_dwordx4 v225, v[188:191], s[40:41] offset:112
	s_add_u32 s63, s63, 1
	s_cmp_lt_u32 s63, s57
	s_cbranch_scc1 .Lav1_lnl
	s_add_u32 s51, s51, 4
	s_cmp_lt_u32 s51, s62
	s_cbranch_scc1 .Lav1_group
